# NSA tile loops: K LDS writes after QK, V writes in PV, next-tile global loads (saddr form) and tile-index SALU issued after the first K-fragment reads instead of before them
# speedup vs baseline: 1.0033x; 1.0023x over previous
; #pragma unroll
;     for (int r = 0; r < 16; ++r) { p0[r] = 0.f; p1[r] = 0.f; }
;     int rowb = r32 * (2 * D), swz = (r32 & 7) << 4; asm volatile("" : "+v"(rowb), "+v"(swz));
; #pragma unroll
;     for (int g4 = 0; g4 < D / (16 * NBT); ++g4) {
;         bf16x8 kf[2 * NBT];
; #pragma unroll
;         for (int i = 0; i < NBT; ++i) { const int cb = ((g4 * NBT + i) * 16 + hi * 8) * 2;
;             const char* kp = Ks + rowb + (cb ^ swz);
;             kf[2 * i] = *reinterpret_cast<const bf16x8*>(kp);
;             kf[2 * i + 1] = *reinterpret_cast<const bf16x8*>(kp + 64 * D); }
; template <int D, bool PIPE, class Seq, class MaskF, class KX>
; DI void run_tiles(Core<D>& c, char* kv, float* ws, const bf16_t* Kg0, const bf16_t* Vg0, int pitch, const Seq& seq, const MaskF& mk, const KX& kx, int tid_, int lane_) {
;     ...
;         for (;;) {
;             int t1 = 0; const bool e1 = seq.next(t0, t1);
;             if (e1) { stg_ld<D>(sk, Kg0 + (size_t)64 * t1 * pitch, pitch, tid); stg_ld<D>(sv, Vg0 + (size_t)64 * t1 * pitch, pitch, tid); }
;             f32x16 p0, p1; qkt<D>(p0, p1, kv + buf * KB, c.qr, r32, hi);
.LBB0_860:
.LBB0_862:
	s_lshl_b32 s61, s10, 14
	v_mov_b32_e32 v0, v171
	v_mov_b32_e32 v177, v204
	s_add_i32 s14, s61, 0
	v_add_u32_e32 v74, 32, v205
	v_add_u32_e32 v0, s14, v0
	v_xad_u32 v70, v177, v205, v0
	v_xad_u32 v74, v177, v74, v0
	ds_read_b128 v[66:69], v70
	ds_read_b128 v[70:73], v70 offset:8192
	ds_read_b128 v[194:197], v74
	ds_read_b128 v[220:223], v74 offset:8192
	v_add_u32_e32 v74, 64, v205
	v_xad_u32 v74, v177, v74, v0
	ds_read_b128 v[224:227], v74
	ds_read_b128 v[228:231], v74 offset:8192
	v_add_u32_e32 v74, 0x60, v205
	v_xad_u32 v74, v177, v74, v0
	ds_read_b128 v[232:235], v74
	ds_read_b128 v[236:239], v74 offset:8192
	s_add_i32 s60, s59, 1
	s_lshr_b64 s[2:3], s[50:51], s60
	s_cmp_lt_i32 s59, 63
	s_cselect_b32 s15, s3, 0
	s_cselect_b32 s14, s2, 0
	s_cmp_lg_u64 s[14:15], 0
	s_cselect_b64 s[52:53], -1, 0
	s_cmp_eq_u64 s[14:15], 0
	s_cselect_b64 s[2:3], -1, 0
	s_ff1_i32_b64 s14, s[14:15]
	s_add_i32 s60, s60, s14
	s_cmp_eq_u64 s[52:53], 0
	s_cbranch_scc1 .Ltl_sel_noload
	s_mul_i32 s17, s60, 0xa0000
	s_add_u32 s14, s4, s17
	s_addc_u32 s15, s5, 0
	s_add_u32 s98, s57, s17
	s_addc_u32 s99, s58, 0
	v_add_u32_e32 v248, v172, v176
	v_add_u32_e32 v249, v174, v176
	global_load_dwordx4 v[98:101], v248, s[14:15]
	global_load_dwordx4 v[102:105], v249, s[14:15]
	global_load_dwordx4 v[106:109], v248, s[98:99]
	global_load_dwordx4 v[144:147], v249, s[98:99]
.Ltl_sel_noload:
	s_waitcnt lgkmcnt(7)
	v_mfma_f32_32x32x16_bf16 v[82:97], v[66:69], v[112:115], 0
	s_waitcnt lgkmcnt(6)
	v_mfma_f32_32x32x16_bf16 v[66:81], v[70:73], v[112:115], 0
	s_waitcnt lgkmcnt(5)
	v_mfma_f32_32x32x16_bf16 v[82:97], v[194:197], v[116:119], v[82:97]
	v_xad_u32 v186, v177, v209, v0
	ds_read_b128 v[194:197], v186
	s_waitcnt lgkmcnt(5)
	v_mfma_f32_32x32x16_bf16 v[66:81], v[220:223], v[116:119], v[66:81]
	ds_read_b128 v[220:223], v186 offset:8192
	v_xad_u32 v186, v177, v210, v0
	s_waitcnt lgkmcnt(5)
	v_mfma_f32_32x32x16_bf16 v[82:97], v[224:227], v[120:123], v[82:97]
	ds_read_b128 v[224:227], v186
	s_waitcnt lgkmcnt(5)
	v_mfma_f32_32x32x16_bf16 v[66:81], v[228:231], v[120:123], v[66:81]
	ds_read_b128 v[228:231], v186 offset:8192
	v_xad_u32 v186, v177, v211, v0
	v_xad_u32 v0, v177, v212, v0
	s_waitcnt lgkmcnt(5)
	v_mfma_f32_32x32x16_bf16 v[82:97], v[232:235], v[124:127], v[82:97]
	ds_read_b128 v[232:235], v186
	s_waitcnt lgkmcnt(5)
	v_mfma_f32_32x32x16_bf16 v[66:81], v[236:239], v[124:127], v[66:81]
	ds_read_b128 v[236:239], v186 offset:8192
	ds_read_b128 v[248:251], v0
	ds_read_b128 v[186:189], v0 offset:8192
	s_waitcnt lgkmcnt(7)
	v_mfma_f32_32x32x16_bf16 v[82:97], v[194:197], v[128:131], v[82:97]
	s_waitcnt lgkmcnt(6)
	v_mfma_f32_32x32x16_bf16 v[66:81], v[220:223], v[128:131], v[66:81]
	s_waitcnt lgkmcnt(5)
	v_mfma_f32_32x32x16_bf16 v[82:97], v[224:227], v[132:135], v[82:97]
	s_waitcnt lgkmcnt(4)
	v_mfma_f32_32x32x16_bf16 v[66:81], v[228:231], v[132:135], v[66:81]
	s_waitcnt lgkmcnt(3)
	v_mfma_f32_32x32x16_bf16 v[82:97], v[232:235], v[136:139], v[82:97]
	s_waitcnt lgkmcnt(2)
	v_mfma_f32_32x32x16_bf16 v[66:81], v[236:239], v[136:139], v[66:81]
	s_waitcnt lgkmcnt(1)
	v_mfma_f32_32x32x16_bf16 v[82:97], v[248:251], v[140:143], v[82:97]
	s_waitcnt lgkmcnt(0)
	v_mfma_f32_32x32x16_bf16 v[66:81], v[186:189], v[140:143], v[66:81]
	s_cmp_eq_u64 s[52:53], 0
	s_cbranch_scc1 .Lew_sel_kskip
	s_xor_b32 s99, s61, 0x4000
	v_add_u32_e32 v194, s99, v208
	s_waitcnt vmcnt(3)
	ds_write_b128 v194, v[98:101]
	s_waitcnt vmcnt(2)
	ds_write_b128 v194, v[102:105] offset:8192

; template <int D, bool PIPE, class Seq, class MaskF, class KX>
; DI void run_tiles(Core<D>& c, char* kv, float* ws, const bf16_t* Kg0, const bf16_t* Vg0, int pitch, const Seq& seq, const MaskF& mk, const KX& kx, int tid_, int lane_) {
;     ...
;         for (;;) {
;             int t1 = 0; const bool e1 = seq.next(t0, t1);
;             if (e1) { stg_ld<D>(sk, Kg0 + (size_t)64 * t1 * pitch, pitch, tid); stg_ld<D>(sv, Vg0 + (size_t)64 * t1 * pitch, pitch, tid); }
;             f32x16 p0, p1; qkt<D>(p0, p1, kv + buf * KB, c.qr, r32, hi);
.LBB0_881:
.LBB0_883:
	s_lshl_b32 s93, s10, 14
	s_add_i32 s14, s93, 0
	v_mov_b32_e32 v66, v175
	v_mov_b32_e32 v217, v176
	v_add_u32_e32 v74, 32, v177
	v_add_u32_e32 v234, s14, v66
	v_xad_u32 v70, v217, v177, v234
	v_xad_u32 v74, v217, v74, v234
	ds_read_b128 v[66:69], v70
	ds_read_b128 v[70:73], v70 offset:8192
	ds_read_b128 v[186:189], v74
	ds_read_b128 v[194:197], v74 offset:8192
	v_add_u32_e32 v74, 64, v177
	v_xad_u32 v74, v217, v74, v234
	ds_read_b128 v[218:221], v74
	ds_read_b128 v[222:225], v74 offset:8192
	v_xad_u32 v74, v217, v206, v234
	ds_read_b128 v[226:229], v74
	ds_read_b128 v[230:233], v74 offset:8192
	s_add_i32 s88, s92, 1
	s_cmp_lt_i32 s92, s91
	s_cselect_b64 s[2:3], -1, 0
	s_cmp_ge_i32 s92, s91
	s_cselect_b64 s[82:83], -1, 0
	s_cmp_eq_u64 s[2:3], 0
	s_cbranch_scc1 .Ltl_win_noload
	s_mul_i32 s17, s88, 0xa0000
	s_add_u32 s14, s94, s17
	s_addc_u32 s15, s4, 0
	s_add_u32 s98, s5, s17
	s_addc_u32 s99, s85, 0
	v_add_u32_e32 v248, v170, v0
	v_add_u32_e32 v249, v172, v0
	global_load_dwordx4 v[98:101], v248, s[14:15]
	global_load_dwordx4 v[102:105], v249, s[14:15]
	global_load_dwordx4 v[106:109], v248, s[98:99]
	global_load_dwordx4 v[144:147], v249, s[98:99]
.Ltl_win_noload:
	s_waitcnt lgkmcnt(7)
	v_mfma_f32_32x32x16_bf16 v[82:97], v[66:69], v[112:115], 0
	s_waitcnt lgkmcnt(6)
	v_mfma_f32_32x32x16_bf16 v[66:81], v[70:73], v[112:115], 0
	s_waitcnt lgkmcnt(5)
	v_mfma_f32_32x32x16_bf16 v[82:97], v[186:189], v[116:119], v[82:97]
	v_xad_u32 v238, v217, v207, v234
	v_xad_u32 v239, v217, v208, v234
	v_xad_u32 v253, v217, v209, v234
	v_xad_u32 v217, v217, v210, v234
	ds_read_b128 v[186:189], v238
	s_waitcnt lgkmcnt(5)
	v_mfma_f32_32x32x16_bf16 v[66:81], v[194:197], v[116:119], v[66:81]
	ds_read_b128 v[194:197], v238 offset:8192
	s_waitcnt lgkmcnt(5)
	v_mfma_f32_32x32x16_bf16 v[82:97], v[218:221], v[120:123], v[82:97]
	ds_read_b128 v[218:221], v239
	s_waitcnt lgkmcnt(5)
	v_mfma_f32_32x32x16_bf16 v[66:81], v[222:225], v[120:123], v[66:81]
	ds_read_b128 v[222:225], v239 offset:8192
	s_waitcnt lgkmcnt(5)
	v_mfma_f32_32x32x16_bf16 v[82:97], v[226:229], v[124:127], v[82:97]
	ds_read_b128 v[226:229], v253
	s_waitcnt lgkmcnt(5)
	v_mfma_f32_32x32x16_bf16 v[66:81], v[230:233], v[124:127], v[66:81]
	ds_read_b128 v[230:233], v253 offset:8192
	ds_read_b128 v[234:237], v217
	ds_read_b128 v[248:251], v217 offset:8192
	s_waitcnt lgkmcnt(7)
	v_mfma_f32_32x32x16_bf16 v[82:97], v[186:189], v[128:131], v[82:97]
	s_waitcnt lgkmcnt(6)
	v_mfma_f32_32x32x16_bf16 v[66:81], v[194:197], v[128:131], v[66:81]
	s_waitcnt lgkmcnt(5)
	v_mfma_f32_32x32x16_bf16 v[82:97], v[218:221], v[132:135], v[82:97]
	s_waitcnt lgkmcnt(4)
	v_mfma_f32_32x32x16_bf16 v[66:81], v[222:225], v[132:135], v[66:81]
	s_waitcnt lgkmcnt(3)
	v_mfma_f32_32x32x16_bf16 v[82:97], v[226:229], v[136:139], v[82:97]
	s_waitcnt lgkmcnt(2)
	v_mfma_f32_32x32x16_bf16 v[66:81], v[230:233], v[136:139], v[66:81]
	s_waitcnt lgkmcnt(1)
	v_mfma_f32_32x32x16_bf16 v[82:97], v[234:237], v[140:143], v[82:97]
	s_waitcnt lgkmcnt(0)
	v_mfma_f32_32x32x16_bf16 v[66:81], v[248:251], v[140:143], v[66:81]
	s_cmp_eq_u64 s[2:3], 0
	s_cbranch_scc1 .Lew_win_kskip
	s_xor_b32 s99, s93, 0x4000
	v_add_u32_e32 v194, s99, v205
	s_waitcnt vmcnt(3)
	ds_write_b128 v194, v[98:101]
	s_waitcnt vmcnt(2)
	ds_write_b128 v194, v[102:105] offset:8192
